# stack3: + COMB o_n loop row prefetch (double-buffered loads, first row issued during setup), conv-item assignment reversed for load balance
# baseline (speedup 1.0000x reference)
; #define GAS __attribute__((address_space(1)))
; __global__ void __launch_bounds__(NWAVES * 64, 2) trunk_fwd(Args args) {
;     ...
;             {   const float* q1 = ka->in[11] + L * HD; const float* k1 = ka->in[12] + L * HD; const float* q2 = ka->in[13] + L * HD; const float* k2 = ka->in[14] + L * HD;
;                 const float s1 = wave_sum(q1[lane] * k1[lane] + q1[lane + 64] * k1[lane + 64]), s2 = wave_sum(q2[lane] * k2[lane] + q2[lane + 64] * k2[lane + 64]);
;                 lam = expf(s1) - expf(s2) + lam_init; }
;             const GAS f32x4* gsp = (const GAS f32x4*)(ka->in[15] + (size_t)L * 256 + (lane & 31) * 8); const f32x4 gs0 = gsp[0], gs1 = gsp[1];
;             const float osc = 1.f - lam_init;
;             for (int m = gw; m < M; m += NGW) {
;                 const bf16* o1 = OP + (size_t)m * DM; const bf16* o2 = OP + (size_t)M * DM + (size_t)m * DM; bf16* orow = ABR + (size_t)m * KBR + DCONV;
;                 v4u aw[4], cw2[4];
; #pragma unroll
;                 for (int i = 0; i < 4; ++i) { aw[i] = ((const GAS v4u*)(o1 + i * 512))[lane]; cw2[i] = ((const GAS v4u*)(o2 + i * 512))[lane]; }
.LBB0_377:
	s_andn2_b64 vcc, exec, s[12:13]
	s_cbranch_vccnz .LBB0_471
	v_readlane_b32 s12, v253, 11
	v_mov_b32_e32 v2, v0
	v_readlane_b32 s13, v253, 12
	s_waitcnt lgkmcnt(0)
	s_mov_b32 s18, s48
	v_readlane_b32 s2, v253, 2
	v_readlane_b32 s3, v253, 4
	v_readlane_b32 s10, v253, 3
	s_load_dwordx4 s[40:43], s[12:13], 0xd8
	v_writelane_b32 v254, s12, 43
	s_load_dwordx8 s[48:55], s[12:13], 0x58
	v_and_b32_e32 v42, 63, v2
	v_writelane_b32 v254, s13, 44
	v_lshlrev_b32_e32 v3, 2, v42
	v_readlane_b32 s38, v254, 36
	s_lshl_b32 s10, s38, 7
	s_lshl_b64 s[2:3], s[10:11], 2
	s_waitcnt lgkmcnt(0)
	s_add_u32 s12, s48, s2
	s_addc_u32 s13, s49, s3
	s_add_u32 s16, s50, s2
	s_addc_u32 s17, s51, s3
	global_load_dword v4, v3, s[16:17]
	global_load_dword v5, v3, s[16:17] offset:256
	global_load_dword v6, v3, s[12:13] offset:256
	global_load_dword v7, v3, s[12:13]
	s_add_u32 s12, s52, s2
	s_addc_u32 s13, s53, s3
	s_add_u32 s2, s54, s2
	s_addc_u32 s3, s55, s3
	v_readlane_b32 s39, v254, 37
	v_readlane_b32 s52, v254, 33
	s_mov_b32 s39, s11
	v_readlane_b32 s53, v254, 34
	v_writelane_b32 v254, s38, 36
	s_cmpk_gt_i32 s18, 0x21ff
	v_lshlrev_b32_e32 v178, 4, v42
	s_mul_i32 s100, s18, 0x1000
	v_lshl_add_u64 v[92:93], s[42:43], 0, v[178:179]
	v_add_co_u32_e32 v92, vcc, s100, v92
	s_nop 1
	v_addc_co_u32_e32 v93, vcc, 0, v93, vcc
	v_add_co_u32_e32 v94, vcc, 0x54900000, v92
	s_nop 1
	v_addc_co_u32_e32 v95, vcc, 0, v93, vcc
	v_add_co_u32_e32 v92, vcc, 0x56b00000, v92
	s_nop 1
	v_addc_co_u32_e32 v93, vcc, 0, v93, vcc
	global_load_dwordx4 v[60:63], v[94:95], off
	global_load_dwordx4 v[64:67], v[92:93], off
	global_load_dwordx4 v[68:71], v[94:95], off offset:1024
	global_load_dwordx4 v[72:75], v[92:93], off offset:1024
	global_load_dwordx4 v[76:79], v[94:95], off offset:2048
	global_load_dwordx4 v[80:83], v[92:93], off offset:2048
	global_load_dwordx4 v[84:87], v[94:95], off offset:3072
	global_load_dwordx4 v[88:91], v[92:93], off offset:3072
	v_writelane_b32 v254, s39, 37
	s_waitcnt vmcnt(0)
	v_mul_f32_e32 v5, v6, v5
	v_fmac_f32_e32 v5, v7, v4
	ds_swizzle_b32 v4, v5 offset:swizzle(SWAP,1)
	v_readlane_b32 s16, v254, 27
	v_readlane_b32 s17, v254, 28
	s_waitcnt lgkmcnt(0)
	v_add_f32_e32 v4, v5, v4
	ds_swizzle_b32 v5, v4 offset:swizzle(SWAP,2)
	s_waitcnt lgkmcnt(0)
	v_add_f32_e32 v4, v4, v5
	ds_swizzle_b32 v5, v4 offset:swizzle(SWAP,4)
	s_waitcnt lgkmcnt(0)
	v_add_f32_e32 v4, v4, v5
	ds_swizzle_b32 v5, v4 offset:swizzle(SWAP,8)
	s_waitcnt lgkmcnt(0)
	v_add_f32_e32 v4, v4, v5
	ds_swizzle_b32 v5, v4 offset:swizzle(SWAP,16)
	s_waitcnt lgkmcnt(0)
	v_add_f32_e32 v12, v4, v5
	v_mov_b32_e32 v13, v12
	global_load_dword v4, v3, s[2:3]
	global_load_dword v5, v3, s[2:3] offset:256
	global_load_dword v6, v3, s[12:13] offset:256
	s_nop 0
	global_load_dword v3, v3, s[12:13]
	v_permlane32_swap_b32_e32 v12, v13
	s_waitcnt vmcnt(1)
	v_mul_f32_e32 v5, v6, v5
	s_waitcnt vmcnt(0)
	v_fmac_f32_e32 v5, v3, v4
	ds_swizzle_b32 v3, v5 offset:swizzle(SWAP,1)
	s_waitcnt lgkmcnt(0)
	v_add_f32_e32 v3, v5, v3
	ds_swizzle_b32 v4, v3 offset:swizzle(SWAP,2)
	s_waitcnt lgkmcnt(0)
	v_add_f32_e32 v3, v3, v4
	ds_swizzle_b32 v4, v3 offset:swizzle(SWAP,4)
	s_waitcnt lgkmcnt(0)
	v_add_f32_e32 v3, v3, v4
	ds_swizzle_b32 v4, v3 offset:swizzle(SWAP,8)
	s_waitcnt lgkmcnt(0)
	v_add_f32_e32 v3, v3, v4
	ds_swizzle_b32 v4, v3 offset:swizzle(SWAP,16)
	s_waitcnt lgkmcnt(0)
	v_add_f32_e32 v10, v3, v4
	v_mov_b32_e32 v11, v10
	s_nop 1
	v_permlane32_swap_b32_e32 v10, v11
	s_cbranch_scc1 .LBB0_381
	v_readlane_b32 s12, v254, 36
	s_mov_b32 s10, 0x3fb8aa3b
	v_readlane_b32 s2, v254, 43
	v_cvt_f32_u32_e32 v3, s12
	v_readlane_b32 s3, v254, 44
	s_load_dwordx2 s[2:3], s[2:3], 0x78
	v_readlane_b32 s13, v254, 37
	v_mul_f32_e32 v3, 0xbe99999a, v3
	v_mul_f32_e32 v4, 0x3fb8aa3b, v3
	v_fma_f32 v5, v3, s10, -v4
	v_rndne_f32_e32 v6, v4
	v_fmac_f32_e32 v5, 0x32a5705f, v3
	v_sub_f32_e32 v4, v4, v6
	v_add_f32_e32 v4, v4, v5
	v_exp_f32_e32 v4, v4
	v_cvt_i32_f32_e32 v5, v6
	s_mov_b32 s19, 0xc2ce8ed0
	v_cmp_ngt_f32_e32 vcc, s19, v3
	s_mov_b32 s38, 0x42b17218
	v_ldexp_f32 v4, v4, v5
	s_lshl_b64 s[12:13], s[12:13], 10
	v_cndmask_b32_e32 v4, 0, v4, vcc
	v_cmp_nlt_f32_e32 vcc, s38, v3
	s_waitcnt lgkmcnt(0)
	s_add_u32 s2, s2, s12
	v_lshlrev_b32_e32 v2, 5, v2
	v_cndmask_b32_e32 v3, v238, v4, vcc
	v_mov_b32_e32 v4, 0x3f4ccccd
	s_addc_u32 s3, s3, s13
	v_and_b32_e32 v6, 0x3e0, v2
	v_fmamk_f32 v14, v3, 0xbf19999a, v4
	global_load_dwordx4 v[2:5], v6, s[2:3] offset:16
	s_nop 0
	global_load_dwordx4 v[6:9], v6, s[2:3]
	v_add_f32_e32 v12, v12, v13
	v_mul_f32_e32 v13, 0x3fb8aa3b, v12
	v_fma_f32 v15, v12, s10, -v13
	v_rndne_f32_e32 v16, v13
	v_fmac_f32_e32 v15, 0x32a5705f, v12
	v_sub_f32_e32 v13, v13, v16
	v_add_f32_e32 v13, v13, v15
	v_exp_f32_e32 v13, v13
	v_cvt_i32_f32_e32 v15, v16
	v_cmp_ngt_f32_e32 vcc, s19, v12
	v_add_f32_e32 v10, v10, v11
	v_mul_f32_e32 v11, 0x3fb8aa3b, v10
	v_ldexp_f32 v13, v13, v15
	v_cndmask_b32_e32 v13, 0, v13, vcc
	v_cmp_nlt_f32_e32 vcc, s38, v12
	v_rndne_f32_e32 v15, v11
	s_mul_i32 s3, s18, 0x1800
	v_cndmask_b32_e32 v12, v238, v13, vcc
	v_fma_f32 v13, v10, s10, -v11
	v_fmac_f32_e32 v13, 0x32a5705f, v10
	v_sub_f32_e32 v11, v11, v15
	v_add_f32_e32 v11, v11, v13
	v_exp_f32_e32 v11, v11
	v_cvt_i32_f32_e32 v13, v15
	v_cmp_ngt_f32_e32 vcc, s19, v10
	s_ashr_i32 s19, s18, 31
	s_mul_hi_i32 s2, s18, 0x1800
	v_ldexp_f32 v11, v11, v13
	v_cndmask_b32_e32 v11, 0, v11, vcc
	v_cmp_nlt_f32_e32 vcc, s38, v10
	s_add_u32 s48, s42, s3
	s_addc_u32 s49, s43, s2
	v_cndmask_b32_e32 v10, v238, v11, vcc
	v_sub_f32_e32 v10, v12, v10
	s_lshl_b64 s[2:3], s[18:19], 12
	v_add_f32_e32 v36, v14, v10
	s_add_u32 s50, s42, s2
	v_sub_f32_e32 v43, 1.0, v14
	v_mov_b32_e32 v37, v36
	v_mov_b32_e32 v10, v36
	v_mov_b32_e32 v11, v36
	s_addc_u32 s51, s43, s3
	s_mov_b32 s10, s18
	s_waitcnt vmcnt(0)
	v_mov_b32_e32 v38, v7
	v_mov_b32_e32 v39, v9
	v_mov_b32_e32 v7, v8
	v_mov_b32_e32 v8, v3
	v_mov_b32_e32 v9, v5
	v_mov_b32_e32 v3, v4
; #define GAS __attribute__((address_space(1)))
; __global__ void __launch_bounds__(NWAVES * 64, 2) trunk_fwd(Args args) {
;     ...
;             for (int m = gw; m < M; m += NGW) {
;                 const bf16* o1 = OP + (size_t)m * DM; const bf16* o2 = OP + (size_t)M * DM + (size_t)m * DM; bf16* orow = ABR + (size_t)m * KBR + DCONV;
;                 v4u aw[4], cw2[4];
; #pragma unroll
;                 for (int i = 0; i < 4; ++i) { aw[i] = ((const GAS v4u*)(o1 + i * 512))[lane]; cw2[i] = ((const GAS v4u*)(o2 + i * 512))[lane]; }
; #pragma unroll
;                 for (int i = 0; i < 4; ++i) {
;                     const f32x4 d0 = (f32x4){bf_lo(aw[i].x), bf_hi(aw[i].x), bf_lo(aw[i].y), bf_hi(aw[i].y)} - lam * (f32x4){bf_lo(cw2[i].x), bf_hi(cw2[i].x), bf_lo(cw2[i].y), bf_hi(cw2[i].y)};
;                     const f32x4 d1 = (f32x4){bf_lo(aw[i].z), bf_hi(aw[i].z), bf_lo(aw[i].w), bf_hi(aw[i].w)} - lam * (f32x4){bf_lo(cw2[i].z), bf_hi(cw2[i].z), bf_lo(cw2[i].w), bf_hi(cw2[i].w)};
;                     const float ss = half_sum(((d0.x * d0.x + d0.y * d0.y) + (d0.z * d0.z + d0.w * d0.w)) + ((d1.x * d1.x + d1.y * d1.y) + (d1.z * d1.z + d1.w * d1.w)));
;                     const float r = osc / sqrtf(ss * (1.f / 256.f) + EPS);
.LBB0_380:
	s_waitcnt vmcnt(4)
	v_mov_b32_e32 v44, v60
	v_mov_b32_e32 v45, v61
	v_mov_b32_e32 v46, v62
	v_mov_b32_e32 v47, v63
	v_mov_b32_e32 v48, v64
	v_mov_b32_e32 v49, v65
	v_mov_b32_e32 v50, v66
	v_mov_b32_e32 v51, v67
	v_mov_b32_e32 v32, v68
	v_mov_b32_e32 v33, v69
	v_mov_b32_e32 v34, v70
	v_mov_b32_e32 v35, v71
	v_mov_b32_e32 v28, v72
	v_mov_b32_e32 v29, v73
	v_mov_b32_e32 v30, v74
	v_mov_b32_e32 v31, v75
	v_mov_b32_e32 v24, v76
	v_mov_b32_e32 v25, v77
	v_mov_b32_e32 v26, v78
	v_mov_b32_e32 v27, v79
	v_mov_b32_e32 v20, v80
	v_mov_b32_e32 v21, v81
	v_mov_b32_e32 v22, v82
	v_mov_b32_e32 v23, v83
	v_mov_b32_e32 v16, v84
	v_mov_b32_e32 v17, v85
	v_mov_b32_e32 v18, v86
	v_mov_b32_e32 v19, v87
	v_mov_b32_e32 v12, v88
	v_mov_b32_e32 v13, v89
	v_mov_b32_e32 v14, v90
	v_mov_b32_e32 v15, v91
	s_add_i32 s10, s10, s52
	s_cmpk_gt_i32 s10, 0x21ff
	s_cbranch_scc1 .Lcomb_nopf
	s_add_u32 s100, s50, s16
	s_addc_u32 s101, s51, s17
	v_lshl_add_u64 v[92:93], s[100:101], 0, v[178:179]
	v_add_co_u32_e32 v94, vcc, 0x54900000, v92
	s_nop 1
	v_addc_co_u32_e32 v95, vcc, 0, v93, vcc
	v_add_co_u32_e32 v92, vcc, 0x56b00000, v92
	s_nop 1
	v_addc_co_u32_e32 v93, vcc, 0, v93, vcc
	global_load_dwordx4 v[60:63], v[94:95], off
	global_load_dwordx4 v[64:67], v[92:93], off
	global_load_dwordx4 v[68:71], v[94:95], off offset:1024
	global_load_dwordx4 v[72:75], v[92:93], off offset:1024
	global_load_dwordx4 v[76:79], v[94:95], off offset:2048
	global_load_dwordx4 v[80:83], v[92:93], off offset:2048
	global_load_dwordx4 v[84:87], v[94:95], off offset:3072
	global_load_dwordx4 v[88:91], v[92:93], off offset:3072
.Lcomb_nopf:
	v_xor_b32_e32 v41, 0x80000000, v11
	v_xor_b32_e32 v40, 0x80000000, v10
	v_lshl_add_u64 v[4:5], s[48:49], 0, v[178:179]
	v_lshlrev_b32_e32 v54, 16, v48
	v_lshlrev_b32_e32 v52, 16, v44
	v_and_b32_e32 v53, 0xffff0000, v44
	v_lshlrev_b32_e32 v44, 16, v45
	v_and_b32_e32 v45, 0xffff0000, v45
	v_and_b32_e32 v55, 0xffff0000, v48
	v_lshlrev_b32_e32 v48, 16, v49
	v_and_b32_e32 v49, 0xffff0000, v49
	v_pk_fma_f32 v[44:45], v[40:41], v[48:49], v[44:45]
	v_pk_fma_f32 v[48:49], v[36:37], v[54:55], v[52:53] neg_lo:[1,0,0] neg_hi:[1,0,0]
	v_lshlrev_b32_e32 v52, 16, v46
	v_and_b32_e32 v53, 0xffff0000, v46
	v_lshlrev_b32_e32 v46, 16, v47
	v_and_b32_e32 v47, 0xffff0000, v47
	v_lshlrev_b32_e32 v54, 16, v50
	v_and_b32_e32 v55, 0xffff0000, v50
	v_lshlrev_b32_e32 v50, 16, v51
	v_and_b32_e32 v51, 0xffff0000, v51
	v_pk_fma_f32 v[46:47], v[40:41], v[50:51], v[46:47]
	v_pk_fma_f32 v[50:51], v[36:37], v[54:55], v[52:53] neg_lo:[1,0,0] neg_hi:[1,0,0]
	v_mov_b32_e32 v54, v49
	v_mov_b32_e32 v55, v51
	v_mov_b32_e32 v52, v48
	v_mov_b32_e32 v53, v50
	v_pk_mul_f32 v[54:55], v[54:55], v[54:55]
	v_mov_b32_e32 v56, v45
	v_mov_b32_e32 v57, v47
	v_pk_fma_f32 v[52:53], v[52:53], v[52:53], v[54:55]
	v_mov_b32_e32 v54, v44
	v_mov_b32_e32 v55, v46
	v_pk_mul_f32 v[56:57], v[56:57], v[56:57]
	s_nop 0
	v_pk_fma_f32 v[54:55], v[54:55], v[54:55], v[56:57]
	s_nop 0
	v_pk_add_f32 v[52:53], v[52:53], v[54:55]
	s_nop 0
	v_add_f32_e32 v52, v52, v53
	ds_swizzle_b32 v53, v52 offset:swizzle(SWAP,1)
	s_waitcnt lgkmcnt(0)
	v_add_f32_e32 v52, v52, v53
	ds_swizzle_b32 v53, v52 offset:swizzle(SWAP,2)
	s_waitcnt lgkmcnt(0)
	v_add_f32_e32 v52, v52, v53
	ds_swizzle_b32 v53, v52 offset:swizzle(SWAP,4)
	s_waitcnt lgkmcnt(0)
	v_add_f32_e32 v52, v52, v53
	ds_swizzle_b32 v53, v52 offset:swizzle(SWAP,8)
	s_waitcnt lgkmcnt(0)
	v_add_f32_e32 v52, v52, v53
	ds_swizzle_b32 v53, v52 offset:swizzle(SWAP,16)
	s_waitcnt lgkmcnt(0)
	v_add_f32_e32 v52, v52, v53
	v_fmamk_f32 v52, v52, 0x3b800000, v1
	v_cmp_gt_f32_e32 vcc, s45, v52
	v_mul_f32_e32 v53, 0x4f800000, v52
	s_nop 0
	v_cndmask_b32_e32 v52, v52, v53, vcc
	v_sqrt_f32_e32 v53, v52
	s_nop 0
	v_add_u32_e32 v54, -1, v53
	v_fma_f32 v55, -v54, v53, v52
	v_cmp_ge_f32_e64 s[38:39], 0, v55
	v_add_u32_e32 v55, 1, v53
	s_nop 0
	v_cndmask_b32_e64 v54, v53, v54, s[38:39]
	v_fma_f32 v53, -v55, v53, v52
	v_cmp_lt_f32_e64 s[38:39], 0, v53
	s_nop 1
	v_cndmask_b32_e64 v53, v54, v55, s[38:39]
	v_mul_f32_e32 v54, 0x37800000, v53
	v_cndmask_b32_e32 v53, v53, v54, vcc
	v_cmp_class_f32_e32 vcc, v52, v237
	s_nop 1
	v_cndmask_b32_e32 v52, v53, v52, vcc
	v_div_scale_f32 v53, s[2:3], v52, v52, v43
	v_rcp_f32_e32 v54, v53
	s_mov_b32 s2, 0x5d100000
	v_fma_f32 v55, -v53, v54, 1.0
	v_fmac_f32_e32 v54, v55, v54
	v_div_scale_f32 v55, vcc, v43, v52, v43
	v_mul_f32_e32 v56, v55, v54
	v_fma_f32 v57, -v53, v56, v55
	v_fmac_f32_e32 v56, v57, v54
	v_fma_f32 v53, -v53, v56, v55
	v_div_fmas_f32 v53, v53, v54, v56
	v_div_fixup_f32 v52, v53, v52, v43
	v_mov_b32_e32 v55, v44
	v_mov_b32_e32 v44, v49
	v_mov_b32_e32 v54, v48
	v_pk_mul_f32 v[44:45], v[44:45], v[52:53] op_sel_hi:[1,0]
	v_mov_b32_e32 v48, v50
	v_mov_b32_e32 v49, v46
	v_mov_b32_e32 v46, v51
	v_pk_mul_f32 v[44:45], v[38:39], v[44:45]
	v_pk_mul_f32 v[48:49], v[48:49], v[52:53] op_sel_hi:[1,0]
	v_pk_mul_f32 v[46:47], v[46:47], v[52:53] op_sel_hi:[1,0]
	v_pk_mul_f32 v[54:55], v[54:55], v[52:53] op_sel_hi:[1,0]
	v_pk_mul_f32 v[48:49], v[2:3], v[48:49]
	v_pk_mul_f32 v[46:47], v[8:9], v[46:47]
	v_bfe_u32 v52, v45, 16, 1
	v_pk_mul_f32 v[54:55], v[6:7], v[54:55]
	v_bfe_u32 v50, v47, 16, 1
	v_bfe_u32 v51, v46, 16, 1
	v_bfe_u32 v53, v44, 16, 1
	v_add3_u32 v45, v45, v52, s57
	v_bfe_u32 v52, v48, 16, 1
	v_add3_u32 v44, v44, v53, s57
	v_add3_u32 v46, v46, v51, s57
	v_add3_u32 v47, v47, v50, s57
	v_bfe_u32 v50, v54, 16, 1
	v_bfe_u32 v51, v55, 16, 1
	v_bfe_u32 v53, v49, 16, 1
	v_add3_u32 v48, v48, v52, s57
	v_add3_u32 v49, v49, v53, s57
	v_add3_u32 v51, v55, v51, s57
	v_add3_u32 v50, v54, v50, s57
	v_lshrrev_b32_e32 v48, 16, v48
	v_lshrrev_b32_e32 v50, 16, v50
; #define GAS __attribute__((address_space(1)))
; __device__ __forceinline__ unsigned pk2(float lo, float hi) { return f2bf(lo) | (f2bf(hi) << 16); }
; __global__ void __launch_bounds__(NWAVES * 64, 2) trunk_fwd(Args args) {
;     ...
;                 for (int i = 0; i < 4; ++i) {
;                     const f32x4 d0 = (f32x4){bf_lo(aw[i].x), bf_hi(aw[i].x), bf_lo(aw[i].y), bf_hi(aw[i].y)} - lam * (f32x4){bf_lo(cw2[i].x), bf_hi(cw2[i].x), bf_lo(cw2[i].y), bf_hi(cw2[i].y)};
;                     const f32x4 d1 = (f32x4){bf_lo(aw[i].z), bf_hi(aw[i].z), bf_lo(aw[i].w), bf_hi(aw[i].w)} - lam * (f32x4){bf_lo(cw2[i].z), bf_hi(cw2[i].z), bf_lo(cw2[i].w), bf_hi(cw2[i].w)};
;                     const float ss = half_sum(((d0.x * d0.x + d0.y * d0.y) + (d0.z * d0.z + d0.w * d0.w)) + ((d1.x * d1.x + d1.y * d1.y) + (d1.z * d1.z + d1.w * d1.w)));
;                     const float r = osc / sqrtf(ss * (1.f / 256.f) + EPS);
;                     v4u w; w.x = pk2(d0.x * r * gs0.x, d0.y * r * gs0.y); w.y = pk2(d0.z * r * gs0.z, d0.w * r * gs0.w); w.z = pk2(d1.x * r * gs1.x, d1.y * r * gs1.y); w.w = pk2(d1.z * r * gs1.z, d1.w * r * gs1.w);
;                     ((GAS v4u*)(orow + i * 512))[lane] = w;
	v_lshrrev_b32_e32 v51, 16, v51
	v_lshrrev_b32_e32 v49, 16, v49
	v_and_or_b32 v46, v46, s33, v48
	v_add_co_u32_e32 v48, vcc, s2, v4
	v_and_or_b32 v47, v47, s33, v49
	v_and_or_b32 v45, v45, s33, v51
	v_and_or_b32 v44, v44, s33, v50
	v_addc_co_u32_e32 v49, vcc, 0, v5, vcc
	global_store_dwordx4 v[48:49], v[44:47], off offset:2048
	s_nop 0
	s_nop 0
	v_lshlrev_b32_e32 v44, 16, v32
	v_and_b32_e32 v45, 0xffff0000, v32
	v_lshlrev_b32_e32 v32, 16, v33
	v_and_b32_e32 v33, 0xffff0000, v33
	s_nop 0
	v_lshlrev_b32_e32 v46, 16, v28
	v_and_b32_e32 v47, 0xffff0000, v28
	v_lshlrev_b32_e32 v28, 16, v29
	v_and_b32_e32 v29, 0xffff0000, v29
	v_pk_fma_f32 v[28:29], v[40:41], v[28:29], v[32:33]
	v_pk_fma_f32 v[32:33], v[36:37], v[46:47], v[44:45] neg_lo:[1,0,0] neg_hi:[1,0,0]
	v_lshlrev_b32_e32 v44, 16, v34
	v_and_b32_e32 v45, 0xffff0000, v34
	v_lshlrev_b32_e32 v34, 16, v35
	v_and_b32_e32 v35, 0xffff0000, v35
	v_lshlrev_b32_e32 v46, 16, v30
	v_and_b32_e32 v47, 0xffff0000, v30
	v_lshlrev_b32_e32 v30, 16, v31
	v_and_b32_e32 v31, 0xffff0000, v31
	v_pk_fma_f32 v[30:31], v[40:41], v[30:31], v[34:35]
	v_pk_fma_f32 v[34:35], v[36:37], v[46:47], v[44:45] neg_lo:[1,0,0] neg_hi:[1,0,0]
	v_mov_b32_e32 v46, v33
	v_mov_b32_e32 v47, v35
	v_mov_b32_e32 v44, v32
	v_mov_b32_e32 v45, v34
	v_pk_mul_f32 v[46:47], v[46:47], v[46:47]
	v_mov_b32_e32 v50, v29
	v_mov_b32_e32 v51, v31
	v_pk_fma_f32 v[44:45], v[44:45], v[44:45], v[46:47]
	v_mov_b32_e32 v46, v28
	v_mov_b32_e32 v47, v30
	v_pk_mul_f32 v[50:51], v[50:51], v[50:51]
	s_nop 0
	v_pk_fma_f32 v[46:47], v[46:47], v[46:47], v[50:51]
	s_nop 0
	v_pk_add_f32 v[44:45], v[44:45], v[46:47]
	s_nop 0
	v_add_f32_e32 v44, v44, v45
	ds_swizzle_b32 v45, v44 offset:swizzle(SWAP,1)
	s_waitcnt lgkmcnt(0)
	v_add_f32_e32 v44, v44, v45
	ds_swizzle_b32 v45, v44 offset:swizzle(SWAP,2)
	s_waitcnt lgkmcnt(0)
	v_add_f32_e32 v44, v44, v45
	ds_swizzle_b32 v45, v44 offset:swizzle(SWAP,4)
	s_waitcnt lgkmcnt(0)
	v_add_f32_e32 v44, v44, v45
	ds_swizzle_b32 v45, v44 offset:swizzle(SWAP,8)
	s_waitcnt lgkmcnt(0)
	v_add_f32_e32 v44, v44, v45
	ds_swizzle_b32 v45, v44 offset:swizzle(SWAP,16)
	s_waitcnt lgkmcnt(0)
	v_add_f32_e32 v44, v44, v45
	v_fmamk_f32 v44, v44, 0x3b800000, v1
	v_cmp_gt_f32_e32 vcc, s45, v44
	v_mul_f32_e32 v45, 0x4f800000, v44
	s_nop 0
	v_cndmask_b32_e32 v44, v44, v45, vcc
	v_sqrt_f32_e32 v45, v44
	s_nop 0
	v_add_u32_e32 v46, -1, v45
	v_fma_f32 v47, -v46, v45, v44
	v_cmp_ge_f32_e64 s[38:39], 0, v47
	v_add_u32_e32 v47, 1, v45
	s_nop 0
	v_cndmask_b32_e64 v46, v45, v46, s[38:39]
	v_fma_f32 v45, -v47, v45, v44
	v_cmp_lt_f32_e64 s[38:39], 0, v45
	s_nop 1
	v_cndmask_b32_e64 v45, v46, v47, s[38:39]
	v_mul_f32_e32 v46, 0x37800000, v45
	v_cndmask_b32_e32 v45, v45, v46, vcc
	v_cmp_class_f32_e32 vcc, v44, v237
	s_nop 1
	v_cndmask_b32_e32 v44, v45, v44, vcc
	v_div_scale_f32 v45, s[2:3], v44, v44, v43
	v_rcp_f32_e32 v46, v45
	s_nop 0
	v_fma_f32 v47, -v45, v46, 1.0
	v_fmac_f32_e32 v46, v47, v46
	v_div_scale_f32 v47, vcc, v43, v44, v43
	v_mul_f32_e32 v50, v47, v46
	v_fma_f32 v51, -v45, v50, v47
	v_fmac_f32_e32 v50, v51, v46
	v_fma_f32 v45, -v45, v50, v47
	v_div_fmas_f32 v45, v45, v46, v50
	v_div_fixup_f32 v44, v45, v44, v43
	v_mov_b32_e32 v47, v28
	v_mov_b32_e32 v28, v33
	v_mov_b32_e32 v33, v30
	v_mov_b32_e32 v30, v35
	v_mov_b32_e32 v46, v32
	v_pk_mul_f32 v[28:29], v[28:29], v[44:45] op_sel_hi:[1,0]
	v_mov_b32_e32 v32, v34
	v_pk_mul_f32 v[30:31], v[30:31], v[44:45] op_sel_hi:[1,0]
	v_pk_mul_f32 v[46:47], v[46:47], v[44:45] op_sel_hi:[1,0]
	v_pk_mul_f32 v[28:29], v[38:39], v[28:29]
	v_pk_mul_f32 v[32:33], v[32:33], v[44:45] op_sel_hi:[1,0]
	v_pk_mul_f32 v[30:31], v[8:9], v[30:31]
	v_pk_mul_f32 v[46:47], v[6:7], v[46:47]
	v_pk_mul_f32 v[32:33], v[2:3], v[32:33]
	v_bfe_u32 v34, v31, 16, 1
	v_bfe_u32 v35, v30, 16, 1
	v_bfe_u32 v44, v29, 16, 1
	v_bfe_u32 v45, v28, 16, 1
	v_add3_u32 v28, v28, v45, s57
	v_add3_u32 v29, v29, v44, s57
	v_add3_u32 v30, v30, v35, s57
	v_add3_u32 v31, v31, v34, s57
	v_bfe_u32 v34, v46, 16, 1
	v_bfe_u32 v35, v47, 16, 1
	v_bfe_u32 v44, v32, 16, 1
	v_bfe_u32 v45, v33, 16, 1
	v_add3_u32 v33, v33, v45, s57
	v_add3_u32 v32, v32, v44, s57
	v_add3_u32 v35, v47, v35, s57
	v_add3_u32 v34, v46, v34, s57
	v_lshrrev_b32_e32 v34, 16, v34
	v_lshrrev_b32_e32 v35, 16, v35
	v_lshrrev_b32_e32 v32, 16, v32
	v_lshrrev_b32_e32 v33, 16, v33
	v_and_or_b32 v31, v31, s33, v33
	v_and_or_b32 v30, v30, s33, v32
	v_and_or_b32 v29, v29, s33, v35
	v_and_or_b32 v28, v28, s33, v34
	global_store_dwordx4 v[48:49], v[28:31], off offset:3072
	s_nop 0
	s_nop 0
	v_lshlrev_b32_e32 v28, 16, v24
	v_and_b32_e32 v29, 0xffff0000, v24
	v_lshlrev_b32_e32 v24, 16, v25
	v_and_b32_e32 v25, 0xffff0000, v25
	s_nop 0
	v_lshlrev_b32_e32 v30, 16, v20
	v_and_b32_e32 v31, 0xffff0000, v20
	v_lshlrev_b32_e32 v20, 16, v21
	v_and_b32_e32 v21, 0xffff0000, v21
	v_pk_fma_f32 v[20:21], v[40:41], v[20:21], v[24:25]
	v_pk_fma_f32 v[24:25], v[36:37], v[30:31], v[28:29] neg_lo:[1,0,0] neg_hi:[1,0,0]
	v_lshlrev_b32_e32 v28, 16, v26
	v_and_b32_e32 v29, 0xffff0000, v26
	v_lshlrev_b32_e32 v26, 16, v27
	v_and_b32_e32 v27, 0xffff0000, v27
	v_lshlrev_b32_e32 v30, 16, v22
	v_and_b32_e32 v31, 0xffff0000, v22
	v_lshlrev_b32_e32 v22, 16, v23
	v_and_b32_e32 v23, 0xffff0000, v23
	v_pk_fma_f32 v[22:23], v[40:41], v[22:23], v[26:27]
	v_pk_fma_f32 v[26:27], v[36:37], v[30:31], v[28:29] neg_lo:[1,0,0] neg_hi:[1,0,0]
	v_mov_b32_e32 v30, v25
	v_mov_b32_e32 v31, v27
	v_mov_b32_e32 v28, v24
	v_mov_b32_e32 v29, v26
	v_pk_mul_f32 v[30:31], v[30:31], v[30:31]
	v_mov_b32_e32 v32, v21
	v_mov_b32_e32 v33, v23
	v_pk_fma_f32 v[28:29], v[28:29], v[28:29], v[30:31]
	v_mov_b32_e32 v30, v20
	v_mov_b32_e32 v31, v22
	v_pk_mul_f32 v[32:33], v[32:33], v[32:33]
	s_nop 0
	v_pk_fma_f32 v[30:31], v[30:31], v[30:31], v[32:33]
	s_nop 0
	v_pk_add_f32 v[28:29], v[28:29], v[30:31]
	s_nop 0
	v_add_f32_e32 v28, v28, v29
	ds_swizzle_b32 v29, v28 offset:swizzle(SWAP,1)
	s_waitcnt lgkmcnt(0)
; #define GAS __attribute__((address_space(1)))
; __device__ __forceinline__ unsigned pk2(float lo, float hi) { return f2bf(lo) | (f2bf(hi) << 16); }
; __global__ void __launch_bounds__(NWAVES * 64, 2) trunk_fwd(Args args) {
;     ...
;                 for (int i = 0; i < 4; ++i) {
;                     const f32x4 d0 = (f32x4){bf_lo(aw[i].x), bf_hi(aw[i].x), bf_lo(aw[i].y), bf_hi(aw[i].y)} - lam * (f32x4){bf_lo(cw2[i].x), bf_hi(cw2[i].x), bf_lo(cw2[i].y), bf_hi(cw2[i].y)};
;                     const f32x4 d1 = (f32x4){bf_lo(aw[i].z), bf_hi(aw[i].z), bf_lo(aw[i].w), bf_hi(aw[i].w)} - lam * (f32x4){bf_lo(cw2[i].z), bf_hi(cw2[i].z), bf_lo(cw2[i].w), bf_hi(cw2[i].w)};
;                     const float ss = half_sum(((d0.x * d0.x + d0.y * d0.y) + (d0.z * d0.z + d0.w * d0.w)) + ((d1.x * d1.x + d1.y * d1.y) + (d1.z * d1.z + d1.w * d1.w)));
;                     const float r = osc / sqrtf(ss * (1.f / 256.f) + EPS);
;                     v4u w; w.x = pk2(d0.x * r * gs0.x, d0.y * r * gs0.y); w.y = pk2(d0.z * r * gs0.z, d0.w * r * gs0.w); w.z = pk2(d1.x * r * gs1.x, d1.y * r * gs1.y); w.w = pk2(d1.z * r * gs1.z, d1.w * r * gs1.w);
;                     ((GAS v4u*)(orow + i * 512))[lane] = w;
	v_add_f32_e32 v28, v28, v29
	ds_swizzle_b32 v29, v28 offset:swizzle(SWAP,2)
	s_waitcnt lgkmcnt(0)
	v_add_f32_e32 v28, v28, v29
	ds_swizzle_b32 v29, v28 offset:swizzle(SWAP,4)
	s_waitcnt lgkmcnt(0)
	v_add_f32_e32 v28, v28, v29
	ds_swizzle_b32 v29, v28 offset:swizzle(SWAP,8)
	s_waitcnt lgkmcnt(0)
	v_add_f32_e32 v28, v28, v29
	ds_swizzle_b32 v29, v28 offset:swizzle(SWAP,16)
	s_waitcnt lgkmcnt(0)
	v_add_f32_e32 v28, v28, v29
	v_fmamk_f32 v28, v28, 0x3b800000, v1
	v_cmp_gt_f32_e32 vcc, s45, v28
	v_mul_f32_e32 v29, 0x4f800000, v28
	s_nop 0
	v_cndmask_b32_e32 v28, v28, v29, vcc
	v_sqrt_f32_e32 v29, v28
	s_nop 0
	v_add_u32_e32 v30, -1, v29
	v_fma_f32 v31, -v30, v29, v28
	v_cmp_ge_f32_e64 s[38:39], 0, v31
	v_add_u32_e32 v31, 1, v29
	s_nop 0
	v_cndmask_b32_e64 v30, v29, v30, s[38:39]
	v_fma_f32 v29, -v31, v29, v28
	v_cmp_lt_f32_e64 s[38:39], 0, v29
	s_nop 1
	v_cndmask_b32_e64 v29, v30, v31, s[38:39]
	v_mul_f32_e32 v30, 0x37800000, v29
	v_cndmask_b32_e32 v29, v29, v30, vcc
	v_cmp_class_f32_e32 vcc, v28, v237
	s_nop 1
	v_cndmask_b32_e32 v28, v29, v28, vcc
	v_div_scale_f32 v29, s[2:3], v28, v28, v43
	v_rcp_f32_e32 v30, v29
	s_mov_b32 s2, 0x5d101000
	v_fma_f32 v31, -v29, v30, 1.0
	v_fmac_f32_e32 v30, v31, v30
	v_div_scale_f32 v31, vcc, v43, v28, v43
	v_mul_f32_e32 v32, v31, v30
	v_fma_f32 v33, -v29, v32, v31
	v_fmac_f32_e32 v32, v33, v30
	v_fma_f32 v29, -v29, v32, v31
	v_div_fmas_f32 v29, v29, v30, v32
	v_div_fixup_f32 v28, v29, v28, v43
	v_mov_b32_e32 v31, v20
	v_mov_b32_e32 v20, v25
	v_mov_b32_e32 v25, v22
	v_mov_b32_e32 v22, v27
	v_mov_b32_e32 v30, v24
	v_pk_mul_f32 v[20:21], v[20:21], v[28:29] op_sel_hi:[1,0]
	v_mov_b32_e32 v24, v26
	v_pk_mul_f32 v[22:23], v[22:23], v[28:29] op_sel_hi:[1,0]
	v_pk_mul_f32 v[30:31], v[30:31], v[28:29] op_sel_hi:[1,0]
	v_pk_mul_f32 v[20:21], v[38:39], v[20:21]
	v_pk_mul_f32 v[24:25], v[24:25], v[28:29] op_sel_hi:[1,0]
	v_pk_mul_f32 v[22:23], v[8:9], v[22:23]
	v_pk_mul_f32 v[30:31], v[6:7], v[30:31]
	v_pk_mul_f32 v[24:25], v[2:3], v[24:25]
	v_bfe_u32 v26, v23, 16, 1
	v_bfe_u32 v27, v22, 16, 1
	v_bfe_u32 v28, v21, 16, 1
	v_bfe_u32 v29, v20, 16, 1
	v_add3_u32 v20, v20, v29, s57
	v_add3_u32 v21, v21, v28, s57
	v_add3_u32 v22, v22, v27, s57
	v_add3_u32 v23, v23, v26, s57
	v_bfe_u32 v26, v30, 16, 1
	v_bfe_u32 v27, v31, 16, 1
	v_bfe_u32 v28, v24, 16, 1
	v_bfe_u32 v29, v25, 16, 1
	v_add3_u32 v25, v25, v29, s57
	v_add3_u32 v24, v24, v28, s57
	v_add3_u32 v27, v31, v27, s57
	v_add3_u32 v26, v30, v26, s57
	v_lshrrev_b32_e32 v26, 16, v26
	v_lshrrev_b32_e32 v27, 16, v27
	v_lshrrev_b32_e32 v24, 16, v24
	v_lshrrev_b32_e32 v25, 16, v25
	v_add_co_u32_e32 v4, vcc, s2, v4
	v_and_or_b32 v23, v23, s33, v25
	v_and_or_b32 v22, v22, s33, v24
	v_and_or_b32 v21, v21, s33, v27
	v_and_or_b32 v20, v20, s33, v26
	v_addc_co_u32_e32 v5, vcc, 0, v5, vcc
	global_store_dwordx4 v[4:5], v[20:23], off
	s_nop 0
	s_nop 0
	v_lshlrev_b32_e32 v20, 16, v16
	v_and_b32_e32 v21, 0xffff0000, v16
	v_lshlrev_b32_e32 v16, 16, v17
	v_and_b32_e32 v17, 0xffff0000, v17
	s_nop 0
	v_lshlrev_b32_e32 v22, 16, v12
	v_and_b32_e32 v23, 0xffff0000, v12
	v_lshlrev_b32_e32 v12, 16, v13
	v_and_b32_e32 v13, 0xffff0000, v13
	v_pk_fma_f32 v[12:13], v[40:41], v[12:13], v[16:17]
	v_pk_fma_f32 v[16:17], v[36:37], v[22:23], v[20:21] neg_lo:[1,0,0] neg_hi:[1,0,0]
	v_lshlrev_b32_e32 v20, 16, v18
	v_and_b32_e32 v21, 0xffff0000, v18
	v_lshlrev_b32_e32 v18, 16, v19
	v_and_b32_e32 v19, 0xffff0000, v19
	v_lshlrev_b32_e32 v22, 16, v14
	v_and_b32_e32 v23, 0xffff0000, v14
	v_lshlrev_b32_e32 v14, 16, v15
	v_and_b32_e32 v15, 0xffff0000, v15
	v_pk_fma_f32 v[14:15], v[40:41], v[14:15], v[18:19]
	v_pk_fma_f32 v[18:19], v[36:37], v[22:23], v[20:21] neg_lo:[1,0,0] neg_hi:[1,0,0]
	v_mov_b32_e32 v22, v17
	v_mov_b32_e32 v23, v19
	v_mov_b32_e32 v20, v16
	v_mov_b32_e32 v21, v18
	v_pk_mul_f32 v[22:23], v[22:23], v[22:23]
	v_mov_b32_e32 v24, v13
	v_mov_b32_e32 v25, v15
	v_pk_fma_f32 v[20:21], v[20:21], v[20:21], v[22:23]
	v_mov_b32_e32 v22, v12
	v_mov_b32_e32 v23, v14
	v_pk_mul_f32 v[24:25], v[24:25], v[24:25]
	s_nop 0
	v_pk_fma_f32 v[22:23], v[22:23], v[22:23], v[24:25]
	s_nop 0
	v_pk_add_f32 v[20:21], v[20:21], v[22:23]
	s_nop 0
	v_add_f32_e32 v20, v20, v21
	ds_swizzle_b32 v21, v20 offset:swizzle(SWAP,1)
	s_waitcnt lgkmcnt(0)
; #define GAS __attribute__((address_space(1)))
; __device__ __forceinline__ unsigned pk2(float lo, float hi) { return f2bf(lo) | (f2bf(hi) << 16); }
; __global__ void __launch_bounds__(NWAVES * 64, 2) trunk_fwd(Args args) {
;     ...
;                 for (int i = 0; i < 4; ++i) {
;                     const f32x4 d0 = (f32x4){bf_lo(aw[i].x), bf_hi(aw[i].x), bf_lo(aw[i].y), bf_hi(aw[i].y)} - lam * (f32x4){bf_lo(cw2[i].x), bf_hi(cw2[i].x), bf_lo(cw2[i].y), bf_hi(cw2[i].y)};
;                     const f32x4 d1 = (f32x4){bf_lo(aw[i].z), bf_hi(aw[i].z), bf_lo(aw[i].w), bf_hi(aw[i].w)} - lam * (f32x4){bf_lo(cw2[i].z), bf_hi(cw2[i].z), bf_lo(cw2[i].w), bf_hi(cw2[i].w)};
;                     const float ss = half_sum(((d0.x * d0.x + d0.y * d0.y) + (d0.z * d0.z + d0.w * d0.w)) + ((d1.x * d1.x + d1.y * d1.y) + (d1.z * d1.z + d1.w * d1.w)));
;                     const float r = osc / sqrtf(ss * (1.f / 256.f) + EPS);
;                     v4u w; w.x = pk2(d0.x * r * gs0.x, d0.y * r * gs0.y); w.y = pk2(d0.z * r * gs0.z, d0.w * r * gs0.w); w.z = pk2(d1.x * r * gs1.x, d1.y * r * gs1.y); w.w = pk2(d1.z * r * gs1.z, d1.w * r * gs1.w);
;                     ((GAS v4u*)(orow + i * 512))[lane] = w;
;                 }
;             }
;             const float* cw = ka->in[10] + (size_t)L * 3 * DCONV;
;             for (int it = gw; it < M / 4; it += NGW) {
;                 const int r0 = it * 4; const bool prompt = r0 < MP;
;                 const int tpos = prompt ? (r0 & (SEQ - 1)) : ((r0 - MP) & (DSEQ - 1)); const int slen = prompt ? SEQ : DSEQ; const int sb = prompt ? (r0 >> 11) : ((r0 - MP) >> 6);
	v_add_f32_e32 v20, v20, v21
	ds_swizzle_b32 v21, v20 offset:swizzle(SWAP,2)
	s_waitcnt lgkmcnt(0)
	v_add_f32_e32 v20, v20, v21
	ds_swizzle_b32 v21, v20 offset:swizzle(SWAP,4)
	s_waitcnt lgkmcnt(0)
	v_add_f32_e32 v20, v20, v21
	ds_swizzle_b32 v21, v20 offset:swizzle(SWAP,8)
	s_waitcnt lgkmcnt(0)
	v_add_f32_e32 v20, v20, v21
	ds_swizzle_b32 v21, v20 offset:swizzle(SWAP,16)
	s_waitcnt lgkmcnt(0)
	v_add_f32_e32 v20, v20, v21
	v_fmamk_f32 v20, v20, 0x3b800000, v1
	v_cmp_gt_f32_e32 vcc, s45, v20
	v_mul_f32_e32 v21, 0x4f800000, v20
	s_nop 0
	v_cndmask_b32_e32 v20, v20, v21, vcc
	v_sqrt_f32_e32 v21, v20
	s_nop 0
	v_add_u32_e32 v22, -1, v21
	v_fma_f32 v23, -v22, v21, v20
	v_cmp_ge_f32_e64 s[38:39], 0, v23
	v_add_u32_e32 v23, 1, v21
	s_nop 0
	v_cndmask_b32_e64 v22, v21, v22, s[38:39]
	v_fma_f32 v21, -v23, v21, v20
	v_cmp_lt_f32_e64 s[38:39], 0, v21
	s_nop 1
	v_cndmask_b32_e64 v21, v22, v23, s[38:39]
	v_mul_f32_e32 v22, 0x37800000, v21
	v_cndmask_b32_e32 v21, v21, v22, vcc
	v_cmp_class_f32_e32 vcc, v20, v237
	s_nop 1
	v_cndmask_b32_e32 v20, v21, v20, vcc
	v_div_scale_f32 v21, s[2:3], v20, v20, v43
	v_rcp_f32_e32 v22, v21
	s_mul_i32 s2, s52, 0x1800
	s_add_u32 s48, s48, s2
	s_mul_hi_i32 s2, s52, 0x1800
	v_fma_f32 v23, -v21, v22, 1.0
	v_fmac_f32_e32 v22, v23, v22
	v_div_scale_f32 v23, vcc, v43, v20, v43
	v_mul_f32_e32 v24, v23, v22
	v_fma_f32 v25, -v21, v24, v23
	v_fmac_f32_e32 v24, v25, v22
	v_fma_f32 v21, -v21, v24, v23
	v_div_fmas_f32 v21, v21, v22, v24
	v_div_fixup_f32 v20, v21, v20, v43
	v_mov_b32_e32 v23, v12
	v_mov_b32_e32 v12, v17
	v_mov_b32_e32 v17, v14
	v_mov_b32_e32 v14, v19
	v_mov_b32_e32 v22, v16
	v_pk_mul_f32 v[12:13], v[12:13], v[20:21] op_sel_hi:[1,0]
	v_mov_b32_e32 v16, v18
	v_pk_mul_f32 v[14:15], v[14:15], v[20:21] op_sel_hi:[1,0]
	v_pk_mul_f32 v[22:23], v[22:23], v[20:21] op_sel_hi:[1,0]
	v_pk_mul_f32 v[12:13], v[38:39], v[12:13]
	v_pk_mul_f32 v[16:17], v[16:17], v[20:21] op_sel_hi:[1,0]
	v_pk_mul_f32 v[14:15], v[8:9], v[14:15]
	v_pk_mul_f32 v[22:23], v[6:7], v[22:23]
	v_pk_mul_f32 v[16:17], v[2:3], v[16:17]
	v_bfe_u32 v18, v15, 16, 1
	v_bfe_u32 v19, v14, 16, 1
	v_bfe_u32 v20, v13, 16, 1
	v_bfe_u32 v21, v12, 16, 1
	v_add3_u32 v12, v12, v21, s57
	v_add3_u32 v13, v13, v20, s57
	v_add3_u32 v14, v14, v19, s57
	v_add3_u32 v15, v15, v18, s57
	v_bfe_u32 v18, v22, 16, 1
	v_bfe_u32 v19, v23, 16, 1
	v_bfe_u32 v20, v16, 16, 1
	v_bfe_u32 v21, v17, 16, 1
	s_addc_u32 s49, s49, s2
	v_add3_u32 v17, v17, v21, s57
	v_add3_u32 v16, v16, v20, s57
	v_add3_u32 v19, v23, v19, s57
	v_add3_u32 v18, v22, v18, s57
	s_add_u32 s50, s50, s16
	v_lshrrev_b32_e32 v18, 16, v18
	v_lshrrev_b32_e32 v19, 16, v19
	v_lshrrev_b32_e32 v16, 16, v16
	v_lshrrev_b32_e32 v17, 16, v17
	s_addc_u32 s51, s51, s17
	v_and_or_b32 v15, v15, s33, v17
	v_and_or_b32 v14, v14, s33, v16
	v_and_or_b32 v13, v13, s33, v19
	v_and_or_b32 v12, v12, s33, v18
	s_cmpk_gt_i32 s10, 0x21ff
	global_store_dwordx4 v[4:5], v[12:15], off offset:1024
	s_cbranch_scc0 .LBB0_380
.LBB0_381:
	s_cmpk_gt_i32 s18, 0x87f
	s_mov_b64 s[50:51], 0x1400
	s_mov_b64 s[54:55], 0x2800
	s_cbranch_scc1 .LBB0_417
	s_sub_i32 s18, s52, s18
	s_add_i32 s18, s18, -1
	v_readlane_b32 s2, v254, 43
	v_readlane_b32 s3, v254, 44
	s_load_dwordx2 s[2:3], s[2:3], 0x50
	v_readlane_b32 s8, v254, 36
	s_mul_i32 s12, s8, 0x3000
	s_mul_hi_u32 s10, s8, 0x3000
	v_lshlrev_b32_e32 v98, 3, v42
	s_waitcnt lgkmcnt(0)
	s_add_u32 s38, s2, s12
	s_addc_u32 s39, s3, s10
	s_add_u32 s2, s42, 0x46f00000
	s_addc_u32 s3, s43, 0
	s_add_u32 s42, s42, 0x5d100000
	s_addc_u32 s43, s43, 0
	s_add_u32 s12, s40, 0x26420000
	s_addc_u32 s13, s41, 0
	v_readlane_b32 s9, v254, 37
	s_add_u32 s19, s40, 0x24400000
	v_lshlrev_b32_e32 v2, 5, v42
	v_mov_b32_e32 v3, v179
	v_or_b32_e32 v108, 0x200, v98
	s_addc_u32 s45, s41, 0
	s_lshl_b32 s16, s8, 2
	v_lshl_add_u64 v[100:101], s[38:39], 0, v[2:3]
	v_lshl_add_u64 v[106:107], s[42:43], 0, v[178:179]
	s_mov_b64 s[8:9], 0x1800
	v_lshlrev_b32_e32 v178, 1, v108
	s_lshl_b32 s10, s18, 2
	v_lshl_add_u64 v[102:103], v[100:101], 0, s[92:93]
	v_lshl_add_u64 v[104:105], v[100:101], 0, s[90:91]
	v_lshl_add_u64 v[110:111], v[100:101], 0, s[8:9]
	v_lshl_add_u64 v[112:113], v[100:101], 0, s[54:55]
	v_lshl_add_u64 v[114:115], s[42:43], 0, v[178:179]
	s_or_b32 s17, s10, 3
	s_branch .LBB0_384
